# scores/softmax epilogue: the eight serialized ssq loads issued together at the first row group
# baseline (speedup 1.0000x reference)
.LBB0_1695:
	s_lshl_b32 s2, s33, 8
	v_add_u32_e32 v132, s2, v193
	v_cndmask_b32_e64 v133, 0, 1, s[36:37]
	v_cmp_ne_u32_e64 s[10:11], 1, v133
	s_andn2_b64 vcc, exec, s[36:37]
	v_ashrrev_i32_e32 v133, 31, v132
	s_mov_b32 s3, 0x800000
	s_cbranch_vccnz .LBB0_1697
	v_lshl_add_u64 v[134:135], v[132:133], 2, s[22:23]
	global_load_dword v243, v[134:135], off offset:64
	global_load_dword v244, v[134:135], off offset:128
	global_load_dword v245, v[134:135], off offset:192
	global_load_dword v246, v[134:135], off offset:512
	global_load_dword v247, v[134:135], off offset:576
	global_load_dword v248, v[134:135], off offset:640
	global_load_dword v249, v[134:135], off offset:704
	global_load_dword v134, v[134:135], off
	s_waitcnt vmcnt(0)
	v_fmamk_f32 v134, v134, 0x3a800000, v227
	v_mul_f32_e32 v135, 0x4b800000, v134
	v_cmp_gt_f32_e32 vcc, s3, v134
	s_nop 1
	v_cndmask_b32_e32 v134, v134, v135, vcc
	v_rsq_f32_e32 v134, v134
	s_nop 0
	v_mul_f32_e32 v135, 0x45800000, v134
	v_cndmask_b32_e32 v134, v134, v135, vcc
	v_mul_f32_e32 v134, 0x3db8aa3b, v134
	s_branch .LBB0_1698

.LBB0_1700:
	s_or_b64 exec, exec, s[0:1]
	s_and_b64 vcc, exec, s[10:11]
	s_cbranch_vccnz .LBB0_1702
	s_waitcnt lgkmcnt(0)
	v_mov_b32_e32 v112, v243
	v_fmamk_f32 v112, v112, 0x3a800000, v227
	v_mul_f32_e32 v113, 0x4b800000, v112
	v_cmp_gt_f32_e32 vcc, s3, v112
	s_nop 1
	v_cndmask_b32_e32 v112, v112, v113, vcc
	v_rsq_f32_e32 v112, v112
	s_nop 0
	v_mul_f32_e32 v113, 0x45800000, v112
	v_cndmask_b32_e32 v112, v112, v113, vcc
	v_mul_f32_e32 v112, 0x3db8aa3b, v112
	s_branch .LBB0_1703

.LBB0_1705:
	s_or_b64 exec, exec, s[0:1]
	s_and_b64 vcc, exec, s[10:11]
	s_cbranch_vccnz .LBB0_1707
	s_waitcnt lgkmcnt(0)
	v_mov_b32_e32 v104, v244
	v_fmamk_f32 v104, v104, 0x3a800000, v227
	v_mul_f32_e32 v105, 0x4b800000, v104
	v_cmp_gt_f32_e32 vcc, s3, v104
	s_nop 1
	v_cndmask_b32_e32 v104, v104, v105, vcc
	v_rsq_f32_e32 v104, v104
	s_nop 0
	v_mul_f32_e32 v105, 0x45800000, v104
	v_cndmask_b32_e32 v104, v104, v105, vcc
	v_mul_f32_e32 v110, 0x3db8aa3b, v104
	s_branch .LBB0_1708

.LBB0_1710:
	s_or_b64 exec, exec, s[0:1]
	s_and_b64 vcc, exec, s[10:11]
	s_cbranch_vccnz .LBB0_1712
	s_waitcnt lgkmcnt(0)
	v_mov_b32_e32 v80, v245
	v_fmamk_f32 v80, v80, 0x3a800000, v227
	v_mul_f32_e32 v81, 0x4b800000, v80
	v_cmp_gt_f32_e32 vcc, s3, v80
	s_nop 1
	v_cndmask_b32_e32 v80, v80, v81, vcc
	v_rsq_f32_e32 v80, v80
	s_nop 0
	v_mul_f32_e32 v81, 0x45800000, v80
	v_cndmask_b32_e32 v80, v80, v81, vcc
	v_mul_f32_e32 v80, 0x3db8aa3b, v80
	s_branch .LBB0_1713

.LBB0_1715:
	s_or_b64 exec, exec, s[0:1]
	s_and_b64 vcc, exec, s[10:11]
	s_cbranch_vccnz .LBB0_1717
	s_waitcnt lgkmcnt(0)
	v_mov_b32_e32 v72, v246
	v_fmamk_f32 v72, v72, 0x3a800000, v227
	v_mul_f32_e32 v73, 0x4b800000, v72
	v_cmp_gt_f32_e32 vcc, s3, v72
	s_nop 1
	v_cndmask_b32_e32 v72, v72, v73, vcc
	v_rsq_f32_e32 v72, v72
	s_nop 0
	v_mul_f32_e32 v73, 0x45800000, v72
	v_cndmask_b32_e32 v72, v72, v73, vcc
	v_mul_f32_e32 v78, 0x3db8aa3b, v72
	s_branch .LBB0_1718

.LBB0_1720:
	s_or_b64 exec, exec, s[0:1]
	s_and_b64 vcc, exec, s[10:11]
	s_cbranch_vccnz .LBB0_1722
	s_waitcnt lgkmcnt(0)
	v_mov_b32_e32 v48, v247
	v_fmamk_f32 v48, v48, 0x3a800000, v227
	v_mul_f32_e32 v49, 0x4b800000, v48
	v_cmp_gt_f32_e32 vcc, s3, v48
	s_nop 1
	v_cndmask_b32_e32 v48, v48, v49, vcc
	v_rsq_f32_e32 v48, v48
	s_nop 0
	v_mul_f32_e32 v49, 0x45800000, v48
	v_cndmask_b32_e32 v48, v48, v49, vcc
	v_mul_f32_e32 v48, 0x3db8aa3b, v48
	s_branch .LBB0_1723

.LBB0_1725:
	s_or_b64 exec, exec, s[0:1]
	s_and_b64 vcc, exec, s[10:11]
	s_cbranch_vccnz .LBB0_1727
	s_waitcnt lgkmcnt(0)
	v_mov_b32_e32 v40, v248
	v_fmamk_f32 v40, v40, 0x3a800000, v227
	v_mul_f32_e32 v41, 0x4b800000, v40
	v_cmp_gt_f32_e32 vcc, s3, v40
	s_nop 1
	v_cndmask_b32_e32 v40, v40, v41, vcc
	v_rsq_f32_e32 v40, v40
	s_nop 0
	v_mul_f32_e32 v41, 0x45800000, v40
	v_cndmask_b32_e32 v40, v40, v41, vcc
	v_mul_f32_e32 v50, 0x3db8aa3b, v40
	s_branch .LBB0_1728

.LBB0_1730:
	s_or_b64 exec, exec, s[0:1]
	s_and_b64 vcc, exec, s[10:11]
	s_cbranch_vccnz .LBB0_1732
	s_waitcnt lgkmcnt(0)
	v_mov_b32_e32 v18, v249
	v_fmamk_f32 v18, v18, 0x3a800000, v227
	v_mul_f32_e32 v19, 0x4b800000, v18
	v_cmp_gt_f32_e32 vcc, s3, v18
	s_nop 1
	v_cndmask_b32_e32 v18, v18, v19, vcc
	v_rsq_f32_e32 v18, v18
	s_nop 0
	v_mul_f32_e32 v19, 0x45800000, v18
	v_cndmask_b32_e32 v18, v18, v19, vcc
	v_mul_f32_e32 v18, 0x3db8aa3b, v18
	s_branch .LBB0_1733
